# attention: cross-lane-group row max via v_permlane16/32_swap instead of ds_bpermute (no LDS round trip); on top of v77
# speedup vs baseline: 1.0123x; 1.0075x over previous
.LBB0_732:
	ds_read_b128 v[110:113], v182
	ds_read_b128 v[122:125], v182 offset:64
	ds_read_b128 v[118:121], v182 offset:3328
	ds_read_b128 v[136:139], v182 offset:128
	ds_read_b128 v[140:143], v182 offset:6656
	ds_read_b128 v[148:151], v182 offset:6720
	ds_read_b128 v[152:155], v182 offset:9984
	ds_read_b128 v[156:159], v182 offset:6784
	s_waitcnt lgkmcnt(7)
	v_mfma_f32_16x16x32_bf16 v[114:117], v[110:113], v[0:3], 0
	ds_read_b128 v[164:167], v182 offset:3392
	ds_read_b128 v[186:189], v182 offset:3456
	ds_read_b128 v[190:193], v182 offset:10048
	ds_read_b128 v[194:197], v182 offset:10112
	s_add_i32 s28, s31, -3
	s_waitcnt lgkmcnt(9)
	v_mfma_f32_16x16x32_bf16 v[130:133], v[118:121], v[0:3], 0
	s_cmp_ge_u32 s28, s30
	v_mfma_f32_16x16x32_bf16 v[114:117], v[122:125], v[4:7], v[114:117]
	s_waitcnt lgkmcnt(7)
	v_mfma_f32_16x16x32_bf16 v[144:147], v[140:143], v[0:3], 0
	s_waitcnt lgkmcnt(5)
	v_mfma_f32_16x16x32_bf16 v[160:163], v[152:155], v[0:3], 0
	s_waitcnt lgkmcnt(3)
	v_mfma_f32_16x16x32_bf16 v[130:133], v[164:167], v[4:7], v[130:133]
	v_mfma_f32_16x16x32_bf16 v[114:117], v[136:139], v[16:19], v[114:117]
	v_mfma_f32_16x16x32_bf16 v[144:147], v[148:151], v[4:7], v[144:147]
	s_waitcnt lgkmcnt(1)
	v_mfma_f32_16x16x32_bf16 v[160:163], v[190:193], v[4:7], v[160:163]
	s_nop 4
	v_max_f32_e32 v80, v115, v115
	v_max_f32_e32 v126, v114, v114
	v_max_f32_e32 v80, v126, v80
	v_mfma_f32_16x16x32_bf16 v[130:133], v[186:189], v[16:19], v[130:133]
	v_max3_f32 v80, v80, v116, v117
	v_mfma_f32_16x16x32_bf16 v[198:201], v[156:159], v[16:19], v[144:147]
	s_waitcnt lgkmcnt(0)
	v_mfma_f32_16x16x32_bf16 v[160:163], v[194:197], v[16:19], v[160:163]
	s_nop 3
	v_max3_f32 v80, v80, v130, v131
	v_max3_f32 v80, v80, v132, v133
	v_max3_f32 v80, v80, v198, v199
	v_max3_f32 v80, v80, v200, v201
	v_mfma_f32_16x16x32_bf16 v[202:205], v[110:113], v[8:11], 0
	v_max3_f32 v80, v80, v160, v161
	v_max3_f32 v80, v80, v162, v163
	v_mov_b32_e32 v126, v80
	s_nop 1
	v_permlane16_swap_b32 v80, v126
	v_mfma_f32_16x16x32_bf16 v[206:209], v[118:121], v[8:11], 0
	s_waitcnt lgkmcnt(0)
	v_max_f32_e32 v126, v126, v126
	v_max_f32_e32 v80, v80, v126
	v_mov_b32_e32 v126, v80
	s_nop 1
	v_permlane32_swap_b32 v80, v126
	v_mfma_f32_16x16x32_bf16 v[140:143], v[140:143], v[8:11], 0
	s_waitcnt lgkmcnt(0)
	v_max_f32_e32 v126, v126, v126
	v_mfma_f32_16x16x32_bf16 v[152:155], v[152:155], v[8:11], 0
	v_max_f32_e32 v80, v80, v126
	v_mul_f32_e32 v80, 0x3e16c740, v80
	v_max_f32_e32 v126, v184, v184
	v_mfma_f32_16x16x32_bf16 v[202:205], v[122:125], v[12:15], v[202:205]
	v_max_f32_e32 v146, v126, v80
	v_fma_f32 v110, v114, s37, -v146
	v_exp_f32_e32 v111, v110
	v_mfma_f32_16x16x32_bf16 v[164:167], v[164:167], v[12:15], v[206:209]
	v_fma_f32 v110, v115, s37, -v146
	v_exp_f32_e32 v113, v110
	v_fma_f32 v110, v116, s37, -v146
	v_mfma_f32_16x16x32_bf16 v[140:143], v[148:151], v[12:15], v[140:143]
	v_exp_f32_e32 v115, v110
	v_fma_f32 v110, v117, s37, -v146
	v_exp_f32_e32 v117, v110
	v_mfma_f32_16x16x32_bf16 v[148:151], v[190:193], v[12:15], v[152:155]
	v_fma_f32 v110, v130, s37, -v146
	v_exp_f32_e32 v119, v110
	v_fma_f32 v110, v131, s37, -v146
	v_mfma_f32_16x16x32_bf16 v[152:155], v[136:139], v[44:47], v[202:205]
	v_exp_f32_e32 v121, v110
	v_fma_f32 v110, v132, s37, -v146
	v_exp_f32_e32 v123, v110
	v_mfma_f32_16x16x32_bf16 v[164:167], v[186:189], v[44:47], v[164:167]
	v_fma_f32 v110, v133, s37, -v146
	s_nop 2
	v_max_f32_e32 v112, v153, v153
	v_max_f32_e32 v114, v152, v152
	v_max_f32_e32 v112, v114, v112
	v_mfma_f32_16x16x32_bf16 v[156:159], v[156:159], v[44:47], v[140:143]
	v_max3_f32 v112, v112, v154, v155
	v_max3_f32 v112, v112, v164, v165
	v_max3_f32 v112, v112, v166, v167
	v_mfma_f32_16x16x32_bf16 v[148:151], v[194:197], v[44:47], v[148:151]
	v_exp_f32_e32 v127, v110
	s_nop 2
	v_max3_f32 v112, v112, v156, v157
	v_max3_f32 v112, v112, v158, v159
	v_fma_f32 v110, v198, s37, -v146
	v_exp_f32_e32 v125, v110
	v_max3_f32 v112, v112, v148, v149
	v_max3_f32 v112, v112, v150, v151
	v_mov_b32_e32 v114, v112
	s_nop 1
	v_permlane16_swap_b32 v112, v114
	v_fma_f32 v110, v199, s37, -v146
	v_exp_f32_e32 v133, v110
	v_fma_f32 v110, v200, s37, -v146
	v_exp_f32_e32 v131, v110
	s_waitcnt lgkmcnt(0)
	v_max_f32_e32 v114, v114, v114
	v_max_f32_e32 v112, v112, v114
	v_fma_f32 v110, v201, s37, -v146
	v_mov_b32_e32 v114, v112
	s_nop 1
	v_permlane32_swap_b32 v112, v114
	v_exp_f32_e32 v135, v110
	v_fma_f32 v110, v160, s37, -v146
	v_exp_f32_e32 v137, v110
	v_fma_f32 v110, v161, s37, -v146
	v_exp_f32_e32 v139, v110
	v_fma_f32 v110, v162, s37, -v146
	v_exp_f32_e32 v141, v110
	v_fma_f32 v110, v163, s37, -v146
	v_exp_f32_e32 v143, v110
	s_waitcnt lgkmcnt(0)
	v_max_f32_e32 v110, v114, v114
	v_max_f32_e32 v110, v112, v110
	v_mul_f32_e32 v110, 0x3e16c740, v110
	v_max_f32_e32 v112, v97, v97
	v_max_f32_e32 v145, v112, v110
	v_sub_f32_e32 v80, v184, v146
	v_sub_f32_e32 v97, v97, v145
	v_fma_f32 v110, v152, s37, -v145
	v_fma_f32 v112, v153, s37, -v145
	v_fma_f32 v114, v154, s37, -v145
	v_fma_f32 v116, v155, s37, -v145
	v_fma_f32 v118, v164, s37, -v145
	v_fma_f32 v120, v165, s37, -v145
	v_fma_f32 v122, v166, s37, -v145
	v_fma_f32 v124, v167, s37, -v145
	v_exp_f32_e32 v80, v80
	v_exp_f32_e32 v110, v110
	v_exp_f32_e32 v112, v112
	v_exp_f32_e32 v114, v114
	v_exp_f32_e32 v116, v116
	v_exp_f32_e32 v118, v118
	v_exp_f32_e32 v120, v120
	v_exp_f32_e32 v122, v122
	v_exp_f32_e32 v126, v124
	v_fma_f32 v136, v148, s37, -v145
	v_fma_f32 v138, v149, s37, -v145
	v_fma_f32 v140, v150, s37, -v145
	v_fma_f32 v142, v151, s37, -v145
	v_exp_f32_e32 v144, v97
	ds_read_b64_tr_b16 v[150:151], v183 offset:15872
	ds_read_b64_tr_b16 v[148:149], v183 offset:13312
	ds_read_b64_tr_b16 v[160:161], v183 offset:13344
	ds_read_b64_tr_b16 v[164:165], v183 offset:13376
	ds_read_b64_tr_b16 v[184:185], v183 offset:13408
	ds_read_b64_tr_b16 v[162:163], v183 offset:15904
	ds_read_b64_tr_b16 v[166:167], v183 offset:15936
	ds_read_b64_tr_b16 v[186:187], v183 offset:15968
	v_fma_f32 v130, v157, s37, -v145
	v_cvt_pk_bf16_f32 v152, v111, v113
	v_cvt_pk_bf16_f32 v153, v115, v117
	v_cvt_pk_bf16_f32 v154, v119, v121
	v_cvt_pk_bf16_f32 v155, v123, v127
	v_fma_f32 v124, v156, s37, -v145
	v_exp_f32_e32 v132, v130
	v_fma_f32 v130, v158, s37, -v145
	v_fma_f32 v134, v159, s37, -v145
	v_pk_mul_f32 v[78:79], v[78:79], v[80:81] op_sel_hi:[1,0]
	v_pk_mul_f32 v[76:77], v[76:77], v[80:81] op_sel_hi:[1,0]
	v_pk_mul_f32 v[74:75], v[74:75], v[80:81] op_sel_hi:[1,0]
	v_pk_mul_f32 v[70:71], v[70:71], v[144:145] op_sel_hi:[1,0]
	v_pk_mul_f32 v[68:69], v[68:69], v[144:145] op_sel_hi:[1,0]
	v_cvt_pk_bf16_f32 v156, v110, v112
	v_cvt_pk_bf16_f32 v157, v114, v116
	v_cvt_pk_bf16_f32 v158, v118, v120
	v_cvt_pk_bf16_f32 v159, v122, v126
	v_pk_mul_f32 v[72:73], v[72:73], v[80:81] op_sel_hi:[1,0]
	v_pk_mul_f32 v[66:67], v[66:67], v[80:81] op_sel_hi:[1,0]
	v_pk_mul_f32 v[64:65], v[64:65], v[80:81] op_sel_hi:[1,0]
	v_pk_mul_f32 v[62:63], v[62:63], v[80:81] op_sel_hi:[1,0]
	v_pk_mul_f32 v[58:59], v[58:59], v[144:145] op_sel_hi:[1,0]
	v_pk_mul_f32 v[56:57], v[56:57], v[144:145] op_sel_hi:[1,0]
	v_pk_mul_f32 v[60:61], v[60:61], v[80:81] op_sel_hi:[1,0]
	v_pk_mul_f32 v[54:55], v[54:55], v[144:145] op_sel_hi:[1,0]
	v_pk_mul_f32 v[52:53], v[52:53], v[144:145] op_sel_hi:[1,0]
	v_pk_mul_f32 v[50:51], v[50:51], v[144:145] op_sel_hi:[1,0]
	v_pk_mul_f32 v[48:49], v[48:49], v[144:145] op_sel_hi:[1,0]
	v_exp_f32_e32 v124, v124
	v_exp_f32_e32 v130, v130
	v_exp_f32_e32 v134, v134
	v_exp_f32_e32 v136, v136
	v_exp_f32_e32 v138, v138
	v_exp_f32_e32 v140, v140
	v_exp_f32_e32 v142, v142
	s_waitcnt lgkmcnt(6)
	v_mfma_f32_16x16x32_bf16 v[76:79], v[148:151], v[152:155], v[76:79]
	v_mfma_f32_16x16x32_bf16 v[68:71], v[148:151], v[156:159], v[68:71]
	s_waitcnt lgkmcnt(2)
	v_mfma_f32_16x16x32_bf16 v[148:151], v[160:163], v[152:155], v[72:75]
	v_mfma_f32_16x16x32_bf16 v[56:59], v[160:163], v[156:159], v[56:59]
	v_cvt_pk_bf16_f32 v160, v125, v133
	v_cvt_pk_bf16_f32 v161, v131, v135
	v_cvt_pk_bf16_f32 v162, v137, v139
	s_waitcnt lgkmcnt(1)
	v_mfma_f32_16x16x32_bf16 v[64:67], v[164:167], v[152:155], v[64:67]
	v_cvt_pk_bf16_f32 v163, v141, v143
	v_mfma_f32_16x16x32_bf16 v[52:55], v[164:167], v[156:159], v[52:55]
	v_cvt_pk_bf16_f32 v164, v124, v132
	v_cvt_pk_bf16_f32 v165, v130, v134
	v_cvt_pk_bf16_f32 v166, v136, v138
	s_waitcnt lgkmcnt(0)
	v_mfma_f32_16x16x32_bf16 v[152:155], v[184:187], v[152:155], v[60:63]
	s_nop 2
	ds_read_b64_tr_b16 v[60:61], v183 offset:18432
	ds_read_b64_tr_b16 v[62:63], v183 offset:20992
	v_cvt_pk_bf16_f32 v167, v140, v142
	v_mfma_f32_16x16x32_bf16 v[156:159], v[184:187], v[156:159], v[48:51]
	s_nop 2
	ds_read_b64_tr_b16 v[48:49], v183 offset:18464
	ds_read_b64_tr_b16 v[184:185], v183 offset:18496
	ds_read_b64_tr_b16 v[188:189], v183 offset:18528
	ds_read_b64_tr_b16 v[50:51], v183 offset:21024
	ds_read_b64_tr_b16 v[186:187], v183 offset:21056
	ds_read_b64_tr_b16 v[190:191], v183 offset:21088
	s_waitcnt lgkmcnt(6)
	v_mfma_f32_16x16x32_bf16 v[76:79], v[60:63], v[160:163], v[76:79]
	v_mfma_f32_16x16x32_bf16 v[72:75], v[60:63], v[164:167], v[68:71]
	s_waitcnt lgkmcnt(2)
	v_mfma_f32_16x16x32_bf16 v[60:63], v[48:51], v[160:163], v[148:151]
	v_mfma_f32_16x16x32_bf16 v[56:59], v[48:51], v[164:167], v[56:59]
	s_waitcnt lgkmcnt(1)
	v_mfma_f32_16x16x32_bf16 v[64:67], v[184:187], v[160:163], v[64:67]
	v_mfma_f32_16x16x32_bf16 v[48:51], v[184:187], v[164:167], v[52:55]
	s_waitcnt lgkmcnt(0)
	v_mfma_f32_16x16x32_bf16 v[68:71], v[188:191], v[160:163], v[152:155]
	v_mfma_f32_16x16x32_bf16 v[52:55], v[188:191], v[164:167], v[156:159]
	s_cbranch_scc1 .LBB0_736
	v_add_u32_e32 v97, v87, v86
	s_waitcnt vmcnt(2)
	ds_write_b128 v97, v[20:23] offset:23552
	s_waitcnt vmcnt(1)
	ds_write_b128 v180, v[24:27] offset:36864
	s_and_saveexec_b64 s[28:29], s[4:5]
	s_cbranch_execz .LBB0_735
	s_waitcnt vmcnt(0)
	ds_write_b128 v181, v[32:35] offset:23680

.LBB0_738:
	s_waitcnt lgkmcnt(0)
	s_barrier
	ds_read_b128 v[148:151], v182 offset:23552
	ds_read_b128 v[162:165], v182 offset:33664
	ds_read_b128 v[156:159], v182 offset:26880
	ds_read_b128 v[192:195], v182 offset:26944
	s_waitcnt lgkmcnt(3)
	v_mfma_f32_16x16x32_bf16 v[152:155], v[148:151], v[0:3], 0
	ds_read_b128 v[196:199], v182 offset:30208
	ds_read_b128 v[200:203], v182 offset:27008
	ds_read_b128 v[208:211], v182 offset:33536
	ds_read_b128 v[212:215], v182 offset:33600
	ds_read_b128 v[220:223], v182 offset:23616
	ds_read_b128 v[224:227], v182 offset:23680
	s_waitcnt lgkmcnt(7)
	v_mfma_f32_16x16x32_bf16 v[186:189], v[156:159], v[0:3], 0
	ds_read_b128 v[228:231], v182 offset:30272
	ds_read_b128 v[232:235], v182 offset:30336
	s_add_i32 s39, s31, -2
	s_cmp_ge_u32 s39, s30
	s_waitcnt lgkmcnt(3)
	v_mfma_f32_16x16x32_bf16 v[152:155], v[220:223], v[4:7], v[152:155]
	v_mfma_f32_16x16x32_bf16 v[204:207], v[196:199], v[0:3], 0
	v_mfma_f32_16x16x32_bf16 v[216:219], v[208:211], v[0:3], 0
	v_mfma_f32_16x16x32_bf16 v[186:189], v[192:195], v[4:7], v[186:189]
	s_waitcnt lgkmcnt(2)
	v_mfma_f32_16x16x32_bf16 v[152:155], v[224:227], v[16:19], v[152:155]
	s_waitcnt lgkmcnt(1)
	v_mfma_f32_16x16x32_bf16 v[204:207], v[228:231], v[4:7], v[204:207]
	v_mfma_f32_16x16x32_bf16 v[216:219], v[212:215], v[4:7], v[216:219]
	s_nop 4
	v_max_f32_e32 v97, v153, v153
	v_max_f32_e32 v147, v152, v152
	v_max_f32_e32 v97, v147, v97
	v_mfma_f32_16x16x32_bf16 v[236:239], v[200:203], v[16:19], v[186:189]
	v_max3_f32 v97, v97, v154, v155
	s_waitcnt lgkmcnt(0)
	v_mfma_f32_16x16x32_bf16 v[204:207], v[232:235], v[16:19], v[204:207]
	v_mfma_f32_16x16x32_bf16 v[216:219], v[162:165], v[16:19], v[216:219]
	s_nop 3
	v_max3_f32 v97, v97, v236, v237
	v_max3_f32 v97, v97, v238, v239
	s_nop 0
	v_max3_f32 v97, v97, v204, v205
	v_max3_f32 v97, v97, v206, v207
	v_mfma_f32_16x16x32_bf16 v[148:151], v[148:151], v[8:11], 0
	v_max3_f32 v97, v97, v216, v217
	v_max3_f32 v97, v97, v218, v219
	v_mov_b32_e32 v147, v97
	s_nop 1
	v_permlane16_swap_b32 v97, v147
	v_mfma_f32_16x16x32_bf16 v[156:159], v[156:159], v[8:11], 0
	s_waitcnt lgkmcnt(0)
	v_max_f32_e32 v147, v147, v147
	v_max_f32_e32 v97, v97, v147
	v_mov_b32_e32 v147, v97
	s_nop 1
	v_permlane32_swap_b32 v97, v147
	v_mfma_f32_16x16x32_bf16 v[208:211], v[208:211], v[8:11], 0
	s_waitcnt lgkmcnt(0)
	v_max_f32_e32 v147, v147, v147
	v_max_f32_e32 v97, v97, v147
	v_mul_f32_e32 v97, 0x3e16c740, v97
	v_max_f32_e32 v147, v146, v146
	v_max_f32_e32 v184, v147, v97
	v_sub_f32_e32 v97, v146, v184
	v_fma_f32 v146, v152, s37, -v184
	v_exp_f32_e32 v186, v146
	v_fma_f32 v146, v153, s37, -v184
	v_exp_f32_e32 v187, v146
	v_fma_f32 v146, v154, s37, -v184
	v_exp_f32_e32 v188, v146
	v_fma_f32 v146, v155, s37, -v184
	v_exp_f32_e32 v189, v146
	v_fma_f32 v146, v236, s37, -v184
	v_exp_f32_e32 v190, v146
	v_fma_f32 v146, v237, s37, -v184
	v_exp_f32_e32 v191, v146
	v_fma_f32 v146, v238, s37, -v184
	v_exp_f32_e32 v147, v146
	v_fma_f32 v146, v239, s37, -v184
	v_mfma_f32_16x16x32_bf16 v[220:223], v[220:223], v[12:15], v[148:151]
	v_exp_f32_e32 v168, v97
	s_nop 0
	v_pk_mul_f32 v[78:79], v[78:79], v[168:169] op_sel_hi:[1,0]
	v_mfma_f32_16x16x32_bf16 v[196:199], v[196:199], v[8:11], 0
	v_exp_f32_e32 v151, v146
	v_fma_f32 v146, v204, s37, -v184
	v_exp_f32_e32 v149, v146
	v_fma_f32 v146, v205, s37, -v184
	v_mfma_f32_16x16x32_bf16 v[192:195], v[192:195], v[12:15], v[156:159]
	v_exp_f32_e32 v155, v146
	v_fma_f32 v146, v206, s37, -v184
	v_exp_f32_e32 v153, v146
	v_fma_f32 v146, v207, s37, -v184
	v_mfma_f32_16x16x32_bf16 v[204:207], v[212:215], v[12:15], v[208:211]
	v_exp_f32_e32 v159, v146
	v_fma_f32 v146, v216, s37, -v184
	v_exp_f32_e32 v157, v146
	v_mfma_f32_16x16x32_bf16 v[208:211], v[224:227], v[44:47], v[220:223]
	v_fma_f32 v146, v217, s37, -v184
	v_exp_f32_e32 v161, v146
	v_fma_f32 v150, v218, s37, -v184
	v_mfma_f32_16x16x32_bf16 v[196:199], v[228:231], v[12:15], v[196:199]
	v_cvt_pk_bf16_f32 v216, v186, v187
	s_nop 2
	v_max_f32_e32 v146, v209, v209
	v_max_f32_e32 v148, v208, v208
	v_mfma_f32_16x16x32_bf16 v[200:203], v[200:203], v[44:47], v[192:195]
	v_max_f32_e32 v146, v148, v146
	v_max3_f32 v146, v146, v210, v211
	v_cvt_pk_bf16_f32 v217, v188, v189
	v_mfma_f32_16x16x32_bf16 v[212:215], v[232:235], v[44:47], v[196:199]
	v_cvt_pk_bf16_f32 v218, v190, v191
	s_nop 2
	v_max3_f32 v146, v146, v200, v201
	v_max3_f32 v146, v146, v202, v203
	v_mfma_f32_16x16x32_bf16 v[204:207], v[162:165], v[44:47], v[204:207]
	v_exp_f32_e32 v163, v150
	v_max3_f32 v146, v146, v212, v213
	v_max3_f32 v146, v146, v214, v215
	v_fma_f32 v150, v219, s37, -v184
	v_exp_f32_e32 v165, v150
	s_nop 2
	v_max3_f32 v146, v146, v204, v205
	v_max3_f32 v146, v146, v206, v207
	v_mov_b32_e32 v148, v146
	s_nop 1
	v_permlane16_swap_b32 v146, v148
	v_pk_mul_f32 v[76:77], v[76:77], v[168:169] op_sel_hi:[1,0]
	v_pk_mul_f32 v[62:63], v[62:63], v[168:169] op_sel_hi:[1,0]
	v_cvt_pk_bf16_f32 v219, v147, v151
	v_pk_mul_f32 v[60:61], v[60:61], v[168:169] op_sel_hi:[1,0]
	s_waitcnt lgkmcnt(0)
	v_max_f32_e32 v148, v148, v148
	v_max_f32_e32 v146, v146, v148
	v_mov_b32_e32 v148, v146
	s_nop 1
	v_permlane32_swap_b32 v146, v148
	v_pk_mul_f32 v[66:67], v[66:67], v[168:169] op_sel_hi:[1,0]
	v_pk_mul_f32 v[64:65], v[64:65], v[168:169] op_sel_hi:[1,0]
	v_pk_mul_f32 v[70:71], v[70:71], v[168:169] op_sel_hi:[1,0]
	v_pk_mul_f32 v[68:69], v[68:69], v[168:169] op_sel_hi:[1,0]
	s_waitcnt lgkmcnt(0)
	v_max_f32_e32 v97, v148, v148
	v_max_f32_e32 v97, v146, v97
	v_mul_f32_e32 v97, 0x3e16c740, v97
	v_max_f32_e32 v146, v145, v145
	v_max_f32_e32 v97, v146, v97
	v_fma_f32 v146, v208, s37, -v97
	v_exp_f32_e32 v192, v146
	v_fma_f32 v146, v209, s37, -v97
	v_exp_f32_e32 v193, v146
	v_fma_f32 v146, v210, s37, -v97
	v_exp_f32_e32 v194, v146
	v_fma_f32 v146, v211, s37, -v97
	v_exp_f32_e32 v195, v146
	v_fma_f32 v146, v200, s37, -v97
	v_exp_f32_e32 v196, v146
	v_fma_f32 v146, v201, s37, -v97
	v_sub_f32_e32 v145, v145, v97
	v_exp_f32_e32 v197, v146
	v_fma_f32 v146, v202, s37, -v97
	v_fma_f32 v148, v203, s37, -v97
	v_exp_f32_e32 v146, v146
	v_exp_f32_e32 v150, v148
	v_fma_f32 v148, v212, s37, -v97
	v_fma_f32 v152, v213, s37, -v97
	v_fma_f32 v162, v206, s37, -v97
	v_fma_f32 v164, v207, s37, -v97
	v_exp_f32_e32 v166, v145
	ds_read_b64_tr_b16 v[200:201], v183 offset:39424
	ds_read_b64_tr_b16 v[198:199], v183 offset:36864
	ds_read_b64_tr_b16 v[206:207], v183 offset:36896
	ds_read_b64_tr_b16 v[210:211], v183 offset:36928
	ds_read_b64_tr_b16 v[220:221], v183 offset:36960
	ds_read_b64_tr_b16 v[208:209], v183 offset:39456
	ds_read_b64_tr_b16 v[212:213], v183 offset:39488
	ds_read_b64_tr_b16 v[222:223], v183 offset:39520
	v_fma_f32 v156, v215, s37, -v97
	v_exp_f32_e32 v154, v152
	v_fma_f32 v152, v214, s37, -v97
	v_exp_f32_e32 v158, v156
	v_fma_f32 v156, v204, s37, -v97
	v_fma_f32 v160, v205, s37, -v97
	v_pk_mul_f32 v[74:75], v[74:75], v[166:167] op_sel_hi:[1,0]
	v_pk_mul_f32 v[72:73], v[72:73], v[166:167] op_sel_hi:[1,0]
	v_cvt_pk_bf16_f32 v202, v192, v193
	v_cvt_pk_bf16_f32 v203, v194, v195
	v_cvt_pk_bf16_f32 v204, v196, v197
	v_cvt_pk_bf16_f32 v205, v146, v150
	v_pk_mul_f32 v[58:59], v[58:59], v[166:167] op_sel_hi:[1,0]
	v_pk_mul_f32 v[56:57], v[56:57], v[166:167] op_sel_hi:[1,0]
	v_pk_mul_f32 v[50:51], v[50:51], v[166:167] op_sel_hi:[1,0]
	v_pk_mul_f32 v[48:49], v[48:49], v[166:167] op_sel_hi:[1,0]
	v_pk_mul_f32 v[54:55], v[54:55], v[166:167] op_sel_hi:[1,0]
	v_pk_mul_f32 v[52:53], v[52:53], v[166:167] op_sel_hi:[1,0]
	v_exp_f32_e32 v148, v148
	v_exp_f32_e32 v152, v152
	v_exp_f32_e32 v156, v156
	v_exp_f32_e32 v160, v160
	v_exp_f32_e32 v162, v162
	v_exp_f32_e32 v164, v164
	s_waitcnt lgkmcnt(6)
	v_mfma_f32_16x16x32_bf16 v[76:79], v[198:201], v[216:219], v[76:79]
	v_mfma_f32_16x16x32_bf16 v[72:75], v[198:201], v[202:205], v[72:75]
	v_cvt_pk_bf16_f32 v198, v149, v155
	v_cvt_pk_bf16_f32 v199, v153, v159
	v_cvt_pk_bf16_f32 v200, v157, v161
	s_waitcnt lgkmcnt(2)
	v_mfma_f32_16x16x32_bf16 v[60:63], v[206:209], v[216:219], v[60:63]
	v_cvt_pk_bf16_f32 v201, v163, v165
	v_mfma_f32_16x16x32_bf16 v[56:59], v[206:209], v[202:205], v[56:59]
	s_waitcnt lgkmcnt(1)
	v_mfma_f32_16x16x32_bf16 v[64:67], v[210:213], v[216:219], v[64:67]
	v_mfma_f32_16x16x32_bf16 v[48:51], v[210:213], v[202:205], v[48:51]
	v_cvt_pk_bf16_f32 v210, v148, v154
	v_cvt_pk_bf16_f32 v211, v152, v158
	v_cvt_pk_bf16_f32 v212, v156, v160
	s_waitcnt lgkmcnt(0)
	v_mfma_f32_16x16x32_bf16 v[206:209], v[220:223], v[216:219], v[68:71]
	s_nop 2
	ds_read_b64_tr_b16 v[68:69], v183 offset:41984
	ds_read_b64_tr_b16 v[70:71], v183 offset:44544
	v_cvt_pk_bf16_f32 v213, v162, v164
	v_mfma_f32_16x16x32_bf16 v[202:205], v[220:223], v[202:205], v[52:55]
	s_nop 2
	ds_read_b64_tr_b16 v[52:53], v183 offset:42016
	ds_read_b64_tr_b16 v[214:215], v183 offset:42048
	ds_read_b64_tr_b16 v[218:219], v183 offset:42080
	ds_read_b64_tr_b16 v[54:55], v183 offset:44576
	ds_read_b64_tr_b16 v[216:217], v183 offset:44608
	ds_read_b64_tr_b16 v[220:221], v183 offset:44640
	s_waitcnt lgkmcnt(6)
	v_mfma_f32_16x16x32_bf16 v[76:79], v[68:71], v[198:201], v[76:79]
	v_mfma_f32_16x16x32_bf16 v[68:71], v[68:71], v[210:213], v[72:75]
	s_waitcnt lgkmcnt(2)
	v_mfma_f32_16x16x32_bf16 v[72:75], v[52:55], v[198:201], v[60:63]
	v_mfma_f32_16x16x32_bf16 v[56:59], v[52:55], v[210:213], v[56:59]
	s_waitcnt lgkmcnt(1)
	v_mfma_f32_16x16x32_bf16 v[64:67], v[214:217], v[198:201], v[64:67]
	v_mfma_f32_16x16x32_bf16 v[52:55], v[214:217], v[210:213], v[48:51]
	s_waitcnt lgkmcnt(0)
	v_mfma_f32_16x16x32_bf16 v[60:63], v[218:221], v[198:201], v[206:209]
	v_mfma_f32_16x16x32_bf16 v[48:51], v[218:221], v[210:213], v[202:205]
	s_cbranch_scc1 .LBB0_742
	s_waitcnt vmcnt(2)
	ds_write_b128 v178, v[28:31]
	s_waitcnt vmcnt(1)
	ds_write_b128 v179, v[36:39] offset:13312
	s_and_saveexec_b64 s[28:29], s[4:5]
	s_cbranch_execz .LBB0_741
	s_waitcnt vmcnt(0)
	ds_write_b128 v181, v[40:43] offset:128
